# attention tiles: the cross-half (lane xor 32) LDS shuffles replaced by v_permlane32_swap sequences (no LDS round trip on the serial chain)
# speedup vs baseline: 1.0004x; 1.0004x over previous
; #define LAS __attribute__((address_space(3)))
; __device__ __forceinline__ void attn_phase(LAS unsigned char* lds, const bf16_t* Q, const bf16_t* Kb, const bf16_t* VT, const bf16_t* Zs, bf16_t* OZ, int vcu, int G) {
;     ...
;     for (int unit = vcu; unit < NU; unit += G) {
;         ATT_DECODE(unit, h, rowbase, q0b, kw0)
;         const int qblk = unit & 31;
;         const int qb = 8 * qblk + w, q0 = 32 * qb;
;         bf16x8 qf[4];
;         { const bf16_t* qp = Q + (rowbase + q0 + ql) * D + h * 64 + 8 * hi;
; #pragma unroll
;           for (int kk = 0; kk < 4; ++kk) qf[kk] = *(const bf16x8*)(qp + 16 * kk); }
;         u32x2 zz[8];
;         { const bf16_t* zp = Zs + (rowbase + q0 + ql) * D + h * 64 + 4 * hi;
; #pragma unroll
;           for (int g4 = 0; g4 < 4; ++g4) { zz[g4] = *(const u32x2*)(zp + 8 * g4); zz[4 + g4] = *(const u32x2*)(zp + 32 + 8 * g4); } }
;         asm volatile("" ::: "memory");
; #pragma unroll
;         for (int i = 0; i < 6; ++i) { const int idx = tid + NTHR * i, r = idx >> 3, c = idx & 7;
;             *(LAS u32x4*)(KL + r * 128 + ((c ^ ((r >> 1) & 7)) << 4)) = sk[i]; }
; #pragma unroll
;         for (int i = 0; i < 6; ++i) { const int idx = tid + NTHR * i, d = idx / 48, ch = idx % 48;
;             { u32x4 v = sv[i]; const int gp = (2 * ch) ^ (d & 31);
;                 if (d & 1) { const u32x4 t = v; v.x = t.z; v.y = t.w; v.z = t.x; v.w = t.y; }
;                 *(LAS u32x4*)(VL + d * 768 + ((gp & ~1) << 3)) = v; } }
;         __syncthreads();
;         { const int nu_ = unit + G < NU ? unit + G : unit; ATT_LOAD_STAGE(nu_); }
.LBB0_540:
	s_ashr_i32 s74, s84, 9
	s_ashr_i32 s75, s74, 31
	s_and_b32 s58, s84, 31
	s_lshl_b64 s[78:79], s[74:75], 13
	s_lshl_b32 s74, s58, 3
	s_and_b32 s59, s89, 31
	s_lshl_b32 s81, s58, 8
	s_add_i32 s90, s74, s85
	s_lshl_b32 s91, s59, 3
	s_addk_i32 s81, 0xff80
	s_lshl_b32 s80, s90, 5
	s_add_u32 s74, s78, s80
	s_addc_u32 s75, s79, 0
	v_or_b32_e32 v190, s74, v142
	s_lshl_b32 s74, s84, 1
	s_and_b32 s92, s74, 0x3c0
	s_mov_b32 s72, s84
	s_lshl_b32 s76, s92, 1
	s_add_i32 s84, s84, s3
	v_mov_b32_e32 v191, s75
	s_cmpk_gt_i32 s84, 0x3ff
	v_lshlrev_b64 v[2:3], 11, v[190:191]
	s_cselect_b64 s[74:75], -1, 0
	s_cmpk_lt_i32 s84, 0x400
	v_lshl_add_u64 v[4:5], s[64:65], 0, v[2:3]
	s_mov_b32 s77, s73
	v_lshl_add_u64 v[2:3], s[66:67], 0, v[2:3]
	s_cselect_b32 s72, s84, s72
	v_lshl_add_u64 v[4:5], v[4:5], 0, s[76:77]
	v_lshl_add_u64 v[2:3], v[2:3], 0, s[76:77]
	v_mov_b32_e32 v163, v145
	s_bfe_u32 s77, s72, 0x40005
	s_ashr_i32 s82, s72, 9
	s_lshl_b32 s72, s72, 8
	v_lshl_add_u64 v[4:5], v[4:5], 0, v[144:145]
	v_lshl_add_u64 v[2:3], v[2:3], 0, v[162:163]
	s_ashr_i32 s83, s82, 31
	s_and_b32 s72, s72, 0x1f00
	global_load_dwordx4 v[114:117], v[4:5], off
	global_load_dwordx4 v[118:121], v[4:5], off offset:32
	global_load_dwordx4 v[122:125], v[4:5], off offset:64
	global_load_dwordx4 v[126:129], v[4:5], off offset:96
	global_load_dwordx2 v[192:193], v[2:3], off
	global_load_dwordx2 v[186:187], v[2:3], off offset:16
	global_load_dwordx2 v[182:183], v[2:3], off offset:32
	global_load_dwordx2 v[178:179], v[2:3], off offset:48
	global_load_dwordx2 v[188:189], v[2:3], off offset:64
	global_load_dwordx2 v[184:185], v[2:3], off offset:80
	global_load_dwordx2 v[180:181], v[2:3], off offset:96
	global_load_dwordx2 v[176:177], v[2:3], off offset:112
	s_waitcnt vmcnt(17)
	v_cndmask_b32_e64 v5, v95, v97, s[48:49]
	v_cndmask_b32_e64 v4, v94, v96, s[48:49]
	v_cndmask_b32_e64 v3, v97, v95, s[48:49]
	v_cndmask_b32_e64 v2, v96, v94, s[48:49]
	s_lshl_b64 s[94:95], s[82:83], 13
	s_add_i32 s93, s72, 0xffffff80
	ds_write_b128 v206, v[66:69]
	ds_write_b128 v207, v[70:73]
	ds_write_b128 v206, v[74:77] offset:16384
	ds_write_b128 v208, v[78:81]
	ds_write_b128 v206, v[82:85] offset:32768
	ds_write_b128 v209, v[86:89]
	ds_write_b128 v210, v[2:5] offset:49152
	s_waitcnt vmcnt(16)
	v_cndmask_b32_e64 v5, v91, v93, s[4:5]
	v_cndmask_b32_e64 v4, v90, v92, s[4:5]
	v_cndmask_b32_e64 v3, v93, v91, s[4:5]
	v_cndmask_b32_e64 v2, v92, v90, s[4:5]
	s_cmp_lg_u32 s72, 0
	ds_write_b128 v211, v[2:5] offset:49152
	s_waitcnt vmcnt(15)
	v_cndmask_b32_e64 v5, v103, v105, s[6:7]
	v_cndmask_b32_e64 v4, v102, v104, s[6:7]
	v_cndmask_b32_e64 v3, v105, v103, s[6:7]
	v_cndmask_b32_e64 v2, v104, v102, s[6:7]
	s_cselect_b32 s96, s93, 0
	ds_write_b128 v212, v[2:5] offset:49152
	s_waitcnt vmcnt(14)
	v_cndmask_b32_e64 v5, v99, v101, s[8:9]
	v_cndmask_b32_e64 v4, v98, v100, s[8:9]
	v_cndmask_b32_e64 v3, v101, v99, s[8:9]
	v_cndmask_b32_e64 v2, v100, v98, s[8:9]
	s_ashr_i32 s97, s96, 31
	ds_write_b128 v213, v[2:5] offset:49152
	s_waitcnt vmcnt(13)
	v_cndmask_b32_e64 v5, v111, v113, s[10:11]
	v_cndmask_b32_e64 v4, v110, v112, s[10:11]
	v_cndmask_b32_e64 v3, v113, v111, s[10:11]
	v_cndmask_b32_e64 v2, v112, v110, s[10:11]
	s_add_u32 s94, s94, s96
	ds_write_b128 v214, v[2:5] offset:49152
	s_waitcnt vmcnt(12)
	v_cndmask_b32_e64 v5, v107, v109, s[12:13]
	v_cndmask_b32_e64 v4, v106, v108, s[12:13]
	v_cndmask_b32_e64 v3, v109, v107, s[12:13]
	v_cndmask_b32_e64 v2, v108, v106, s[12:13]
	s_addc_u32 s95, s95, s97
	ds_write_b128 v215, v[2:5] offset:49152
	s_lshl_b32 s72, s77, 7
	v_mov_b32_e32 v5, s95
	v_or_b32_e32 v4, s94, v146
	v_mov_b32_e32 v7, s95
	v_or_b32_e32 v6, s94, v148
	v_lshl_add_u64 v[2:3], v[158:159], 0, s[72:73]
	v_lshlrev_b64 v[4:5], 11, v[4:5]
	v_lshlrev_b64 v[6:7], 11, v[6:7]
	v_lshl_add_u64 v[4:5], v[2:3], 0, v[4:5]
	v_lshl_add_u64 v[6:7], v[2:3], 0, v[6:7]
	s_waitcnt lgkmcnt(0)
	s_barrier
	global_load_dwordx4 v[66:69], v[4:5], off
	global_load_dwordx4 v[70:73], v[6:7], off
	v_lshl_add_u64 v[4:5], s[94:95], 0, v[150:151]
	v_lshl_add_u64 v[6:7], s[94:95], 0, v[152:153]
	v_lshlrev_b64 v[4:5], 11, v[4:5]
	v_lshlrev_b64 v[6:7], 11, v[6:7]
	v_lshl_add_u64 v[4:5], v[2:3], 0, v[4:5]
	v_lshl_add_u64 v[6:7], v[2:3], 0, v[6:7]
	global_load_dwordx4 v[74:77], v[4:5], off
	global_load_dwordx4 v[78:81], v[6:7], off
	v_lshl_add_u64 v[4:5], s[94:95], 0, v[154:155]
	v_lshl_add_u64 v[6:7], s[94:95], 0, v[156:157]
	s_lshl_b32 s72, s77, 20
	s_lshl_b64 s[82:83], s[82:83], 14
	v_lshlrev_b64 v[4:5], 11, v[4:5]
	v_lshlrev_b64 v[6:7], 11, v[6:7]
	s_add_u32 s77, s68, s82
	v_lshl_add_u64 v[4:5], v[2:3], 0, v[4:5]
	v_lshl_add_u64 v[2:3], v[2:3], 0, v[6:7]
	s_addc_u32 s93, s69, s83
	s_lshl_b64 s[82:83], s[96:97], 1
	global_load_dwordx4 v[82:85], v[4:5], off
	global_load_dwordx4 v[86:89], v[2:3], off
	s_add_u32 s82, s77, s82
	v_or_b32_e32 v2, s72, v196
	s_addc_u32 s83, s93, s83
	v_lshlrev_b32_e32 v2, 1, v2
	v_mov_b32_e32 v3, v145
	v_or_b32_e32 v4, s72, v197
	v_lshl_add_u64 v[2:3], s[82:83], 0, v[2:3]
	v_mov_b32_e32 v165, v145
	v_lshlrev_b32_e32 v4, 1, v4
	v_mov_b32_e32 v5, v145
	v_lshl_add_u64 v[2:3], v[2:3], 0, v[164:165]
	v_lshl_add_u64 v[4:5], s[82:83], 0, v[4:5]
	v_mov_b32_e32 v167, v145
	v_lshl_add_u64 v[4:5], v[4:5], 0, v[166:167]
	global_load_dwordx4 v[94:97], v[2:3], off
	global_load_dwordx4 v[90:93], v[4:5], off
	v_or_b32_e32 v2, s72, v198
	v_lshlrev_b32_e32 v2, 1, v2
	v_mov_b32_e32 v3, v145
	v_or_b32_e32 v4, s72, v199
	v_lshl_add_u64 v[2:3], s[82:83], 0, v[2:3]
	v_mov_b32_e32 v169, v145
	v_lshlrev_b32_e32 v4, 1, v4
	v_mov_b32_e32 v5, v145
	v_lshl_add_u64 v[2:3], v[2:3], 0, v[168:169]
	v_lshl_add_u64 v[4:5], s[82:83], 0, v[4:5]
	v_mov_b32_e32 v171, v145
	v_lshl_add_u64 v[4:5], v[4:5], 0, v[170:171]
	global_load_dwordx4 v[102:105], v[2:3], off
	global_load_dwordx4 v[98:101], v[4:5], off
	v_or_b32_e32 v2, s72, v200
	v_lshlrev_b32_e32 v2, 1, v2
	v_mov_b32_e32 v3, v145
	v_or_b32_e32 v4, s72, v201
	v_lshl_add_u64 v[2:3], s[82:83], 0, v[2:3]
	v_mov_b32_e32 v173, v145
	v_lshlrev_b32_e32 v4, 1, v4
	v_mov_b32_e32 v5, v145
	v_lshl_add_u64 v[2:3], v[2:3], 0, v[172:173]
	v_lshl_add_u64 v[4:5], s[82:83], 0, v[4:5]
	v_mov_b32_e32 v175, v145
	v_lshl_add_u64 v[4:5], v[4:5], 0, v[174:175]
	global_load_dwordx4 v[110:113], v[2:3], off
	global_load_dwordx4 v[106:109], v[4:5], off
	s_cmp_lg_u32 s58, 0
	s_cselect_b32 s58, s81, 0
	s_cmp_lt_i32 s80, s58
	s_cbranch_scc1 .LBB0_552
	s_sub_i32 s72, s80, s58
	v_or_b32_e32 v2, s72, v142
	v_lshrrev_b32_e32 v27, 1, v2
	v_lshl_add_u32 v26, v2, 7, 0
	v_bitop3_b32 v2, v27, v1, 7 bitop3:0x6c
	v_lshl_add_u32 v2, v2, 4, v26
	ds_read_b128 v[2:5], v2
	s_lshr_b32 s77, s72, 2
	v_bitop3_b32 v6, s77, v142, v1 bitop3:0x36
	v_lshlrev_b32_e32 v30, 3, v6
	v_bitop3_b32 v6, v27, v143, 7 bitop3:0x6c
	v_lshl_add_u32 v6, v6, 4, v26
	ds_read_b128 v[18:21], v6
	v_or_b32_e32 v28, s77, v1
	s_waitcnt vmcnt(23) lgkmcnt(1)
	v_mfma_f32_32x32x16_bf16 v[2:17], v[2:5], v[114:117], 0
	v_bitop3_b32 v22, v28, v142, 2 bitop3:0x36
	v_lshlrev_b32_e32 v32, 3, v22
	v_bitop3_b32 v22, v28, v142, 4 bitop3:0x36
	v_lshlrev_b32_e32 v38, 3, v22
	v_bitop3_b32 v22, v27, v147, 7 bitop3:0x6c
	v_lshl_add_u32 v22, v22, 4, v26
	ds_read_b128 v[22:25], v22
	s_waitcnt vmcnt(22) lgkmcnt(1)
	v_mfma_f32_32x32x16_bf16 v[2:17], v[18:21], v[118:121], v[2:17]
	v_bitop3_b32 v18, v28, v142, 6 bitop3:0x36
	v_lshlrev_b32_e32 v39, 3, v18
	v_bitop3_b32 v18, v27, v149, 7 bitop3:0x6c
	v_lshl_add_u32 v18, v18, 4, v26
	ds_read_b128 v[26:29], v18
	v_add_u32_e32 v31, v202, v30
	v_add_u32_e32 v34, v202, v38
	s_waitcnt vmcnt(21) lgkmcnt(1)
	v_mfma_f32_32x32x16_bf16 v[2:17], v[22:25], v[122:125], v[2:17]
	v_add_u32_e32 v36, v202, v39
	v_add_u32_e32 v22, v203, v30
	v_add_u32_e32 v24, v203, v38
	v_add_u32_e32 v33, v202, v32
	ds_read_b64 v[18:19], v31 offset:49152
	ds_read_b64 v[20:21], v33 offset:49152
	ds_read_b64 v[34:35], v34 offset:49152
	ds_read_b64 v[36:37], v36 offset:49152
	v_add_u32_e32 v23, v203, v32
	v_add_u32_e32 v25, v203, v39
	s_waitcnt vmcnt(20) lgkmcnt(4)
	v_mfma_f32_32x32x16_bf16 v[2:17], v[26:29], v[126:129], v[2:17]
	ds_read_b64 v[42:43], v22 offset:24576
	ds_read_b64 v[44:45], v23 offset:24576
	ds_read_b64 v[38:39], v24 offset:24576
	ds_read_b64 v[40:41], v25 offset:24576
	v_and_b32_e32 v48, 64, v216
	v_add_u32_e32 v48, 64, v48
	s_mov_b64 s[80:81], 0
	s_nop 4
	v_min_f32_e64 v3, -v3, s98
	v_exp_f32_e32 v3, v3
	v_min_f32_e64 v4, -v4, s98
	v_exp_f32_e32 v24, v4
	v_add_f32_e32 v22, 1.0, v3
	v_min_f32_e64 v4, -v5, s98
	v_rcp_f32_e32 v22, v22
	v_exp_f32_e32 v5, v4
	v_add_f32_e32 v4, 1.0, v24
	v_mul_f32_e32 v3, v3, v22
	v_rcp_f32_e32 v25, v4
	v_cndmask_b32_e64 v4, 1.0, v3, s[16:17]
	v_add_f32_e32 v3, 1.0, v5
	v_min_f32_e64 v2, -v2, s98
	v_rcp_f32_e32 v3, v3
	v_exp_f32_e32 v2, v2
	v_mul_f32_e32 v24, v24, v25
	v_cndmask_b32_e64 v46, 1.0, v24, s[18:19]
	v_mul_f32_e32 v5, v5, v3
	v_cndmask_b32_e64 v24, 0, v3, s[20:21]
	v_min_f32_e64 v3, -v6, s98
	v_min_f32_e64 v6, -v7, s98
	v_add_f32_e32 v26, 1.0, v2
	v_exp_f32_e32 v3, v3
	v_rcp_f32_e32 v26, v26
	v_exp_f32_e32 v7, v6
	v_add_f32_e32 v6, 1.0, v3
	v_cndmask_b32_e64 v22, 0, v22, s[16:17]
	v_mul_f32_e32 v2, v2, v26
	v_cndmask_b32_e64 v23, 0, v26, s[14:15]
	v_rcp_f32_e32 v26, v6
	v_cndmask_b32_e64 v6, 1.0, v5, s[20:21]
	v_add_f32_e32 v5, 1.0, v7
	v_rcp_f32_e32 v5, v5
	v_mul_f32_e32 v3, v3, v26
	v_cndmask_b32_e64 v3, 1.0, v3, s[22:23]
	v_cndmask_b32_e64 v2, 1.0, v2, s[14:15]
	v_mul_f32_e32 v7, v7, v5
	v_cndmask_b32_e64 v27, 0, v5, s[24:25]
	v_min_f32_e64 v5, -v8, s98
	v_min_f32_e64 v8, -v9, s98
	v_exp_f32_e32 v5, v5
	v_exp_f32_e32 v8, v8
	v_cndmask_b32_e64 v28, 1.0, v7, s[24:25]
	v_add_f32_e32 v9, 1.0, v5
	v_rcp_f32_e32 v9, v9
	v_add_f32_e32 v7, 1.0, v8
	v_rcp_f32_e32 v7, v7
	v_mul_f32_e32 v3, v3, v28
	v_mul_f32_e32 v5, v5, v9
	v_cndmask_b32_e64 v30, 1.0, v5, s[26:27]
	v_mul_f32_e32 v5, v8, v7
	v_min_f32_e64 v8, -v11, s98
	v_cndmask_b32_e64 v31, 0, v7, s[28:29]
	v_min_f32_e64 v7, -v10, s98
	v_exp_f32_e32 v8, v8
	v_exp_f32_e32 v7, v7
	v_cndmask_b32_e64 v10, 1.0, v5, s[28:29]
	v_cndmask_b32_e64 v29, 0, v9, s[26:27]
	v_add_f32_e32 v5, 1.0, v8
	v_add_f32_e32 v9, 1.0, v7
	v_rcp_f32_e32 v5, v5
	v_rcp_f32_e32 v9, v9
	v_cndmask_b32_e64 v25, 0, v25, s[18:19]
	v_cndmask_b32_e64 v26, 0, v26, s[22:23]
	v_mul_f32_e32 v8, v8, v5
	v_cndmask_b32_e64 v51, 0, v5, s[34:35]
	v_min_f32_e64 v5, -v12, s98
	v_mul_f32_e32 v7, v7, v9
	v_cndmask_b32_e64 v50, 0, v9, s[30:31]
	v_min_f32_e64 v9, -v13, s98
	v_exp_f32_e32 v5, v5
	v_exp_f32_e32 v9, v9
	v_cndmask_b32_e64 v12, 1.0, v8, s[34:35]
	v_add_f32_e32 v11, 1.0, v5
	v_rcp_f32_e32 v11, v11
	v_add_f32_e32 v8, 1.0, v9
	v_rcp_f32_e32 v8, v8
	v_cndmask_b32_e64 v7, 1.0, v7, s[30:31]
	v_mul_f32_e32 v5, v5, v11
	v_cndmask_b32_e64 v52, 0, v11, s[36:37]
	v_cndmask_b32_e64 v11, 1.0, v5, s[36:37]
	v_mul_f32_e32 v5, v9, v8
	v_min_f32_e64 v9, -v15, s98
	v_exp_f32_e32 v9, v9
	v_cndmask_b32_e64 v15, 1.0, v5, s[38:39]
	v_cndmask_b32_e64 v13, 0, v8, s[38:39]
	v_min_f32_e64 v8, -v14, s98
	v_add_f32_e32 v5, 1.0, v9
	v_rcp_f32_e32 v5, v5
	v_exp_f32_e32 v8, v8
	v_mul_f32_e32 v7, v7, v12
	v_mul_f32_e32 v9, v9, v5
	v_cndmask_b32_e64 v32, 0, v5, s[42:43]
	v_min_f32_e64 v5, -v16, s98
	v_min_f32_e64 v16, -v17, s98
	v_exp_f32_e32 v5, v5
	v_exp_f32_e32 v16, v16
	v_add_f32_e32 v14, 1.0, v8
	v_add_f32_e32 v17, 1.0, v5
	v_rcp_f32_e32 v17, v17
	v_add_f32_e32 v33, 1.0, v16
	v_rcp_f32_e32 v33, v33
	v_rcp_f32_e32 v14, v14
	v_mul_f32_e32 v5, v5, v17
	v_cndmask_b32_e64 v47, 1.0, v5, s[44:45]
	v_mul_f32_e32 v5, v16, v33
	v_mul_f32_e32 v8, v8, v14
	v_cndmask_b32_e64 v16, 0, v33, s[46:47]
	v_cndmask_b32_e64 v33, 1.0, v5, s[46:47]
	v_xor_b32_e32 v5, 32, v216
	v_cndmask_b32_e64 v8, 1.0, v8, s[40:41]
	v_cndmask_b32_e64 v9, 1.0, v9, s[42:43]
	v_cmp_lt_i32_e32 vcc, v5, v48
	v_mul_f32_e32 v8, v8, v9
	v_mul_f32_e32 v48, v47, v33
	v_cndmask_b32_e32 v5, v216, v5, vcc
	v_lshlrev_b32_e32 v163, 2, v5
	v_mul_f32_e32 v8, v8, v48
	v_mov_b32_e32 v238, v8
	v_mov_b32_e32 v48, v8
	s_nop 1
	v_permlane32_swap_b32_e32 v238, v48
	s_nop 0
	v_cndmask_b32_e64 v48, v238, v48, s[0:1]
	v_mul_f32_e32 v49, v11, v15
	v_mul_f32_e32 v5, v30, v10
	v_mul_f32_e32 v7, v7, v49
	v_mul_f32_e32 v3, v3, v5
	v_mov_b32_e32 v238, v7
	v_mov_b32_e32 v53, v7
	s_nop 1
	v_permlane32_swap_b32_e32 v238, v53
	s_nop 0
	v_cndmask_b32_e64 v53, v238, v53, s[0:1]
	v_mov_b32_e32 v238, v3
	v_mov_b32_e32 v5, v3
	s_nop 1
	v_permlane32_swap_b32_e32 v238, v5
	s_nop 0
	v_cndmask_b32_e64 v5, v238, v5, s[0:1]
	s_waitcnt lgkmcnt(2)
; __device__ __forceinline__ void attn_phase(LAS unsigned char* lds, const bf16_t* Q, const bf16_t* Kb, const bf16_t* VT, const bf16_t* Zs, bf16_t* OZ, int vcu, int G) {
;     ...
;         int kt = qb; bool done = false;
;     ...
;             ATT_TILE(true)
;             if (__all(carry < STOP)) { done = true; break; }
;         }
	v_cndmask_b32_e64 v49, 1.0, v48, s[0:1]
	v_mul_f32_e32 v33, v33, v49
	v_mul_f32_e32 v47, v47, v33
	v_mul_f32_e32 v54, v9, v47
	v_mul_f32_e32 v57, v32, v47
	v_mul_f32_e32 v47, v8, v48
	s_waitcnt lgkmcnt(1)
	v_mul_f32_e32 v7, v7, v53
	v_pk_mul_f32 v[8:9], v[46:47], v[6:7]
	s_waitcnt lgkmcnt(0)
	v_pk_mul_f32 v[2:3], v[2:3], v[4:5]
	v_mul_f32_e32 v55, v16, v49
	v_pk_mul_f32 v[48:49], v[2:3], v[8:9]
	v_mov_b32_e32 v238, v48
	v_mov_b32_e32 v58, v48
	s_nop 1
	v_permlane32_swap_b32_e32 v238, v58
	s_nop 0
	v_cndmask_b32_e64 v58, v238, v58, s[0:1]
	v_mul_f32_e32 v2, v9, v5
	v_cndmask_b32_e64 v2, v9, v2, s[0:1]
	v_mul_f32_e32 v3, v10, v2
	v_mul_f32_e32 v8, v31, v2
	s_waitcnt lgkmcnt(0)
	v_mul_f32_e32 v2, v49, v58
	v_cndmask_b32_e64 v2, v49, v2, s[0:1]
	v_mul_f32_e32 v5, v30, v3
	v_mul_f32_e32 v9, v29, v3
	v_mul_f32_e32 v3, v6, v2
	v_mul_f32_e32 v6, v46, v3
	v_mul_f32_e32 v4, v4, v6
	v_mul_f32_e32 v10, v24, v2
	v_mul_f32_e32 v2, v22, v6
	v_mul_f32_e32 v6, v47, v53
	v_mul_f32_e32 v7, v28, v5
	v_cndmask_b32_e64 v6, v47, v6, s[0:1]
	v_mul_f32_e32 v5, v27, v5
	v_mul_f32_e32 v7, v26, v7
	v_mul_f32_e32 v3, v25, v3
	v_mul_f32_e32 v4, v23, v4
	v_mul_f32_e32 v47, v15, v6
	v_cndmask_b32_e64 v14, 0, v14, s[40:41]
	v_cndmask_b32_e64 v17, 0, v17, s[44:45]
	v_cvt_pk_bf16_f32 v2, v4, v2
	v_cvt_pk_bf16_f32 v3, v3, v10
	v_cvt_pk_bf16_f32 v4, v7, v5
	v_cvt_pk_bf16_f32 v5, v9, v8
	v_mul_f32_e32 v53, v11, v47
	v_mul_f32_e32 v56, v17, v33
	v_mfma_f32_32x32x16_bf16 v[18:33], v[18:21], v[2:5], 0
	v_mul_f32_e32 v46, v14, v54
	v_mul_f32_e32 v54, v12, v53
	v_mul_f32_e32 v59, v13, v6
	v_mfma_f32_32x32x16_bf16 v[2:17], v[42:45], v[2:5], 0
	v_mul_f32_e32 v43, v52, v47
	v_mul_f32_e32 v42, v51, v53
	v_mul_f32_e32 v44, v50, v54
	v_cvt_pk_bf16_f32 v42, v44, v42
	v_cvt_pk_bf16_f32 v43, v43, v59
	v_cvt_pk_bf16_f32 v44, v46, v57
	v_cvt_pk_bf16_f32 v45, v56, v55
	s_nop 1
	v_mfma_f32_32x32x16_bf16 v[18:33], v[34:37], v[42:45], v[18:33]
	v_mul_f32_e32 v34, v48, v58
	v_mul_f32_e32 v131, v34, v49
	v_cmp_gt_f32_e32 vcc, s88, v131
	s_cmp_eq_u64 vcc, exec
	v_mfma_f32_32x32x16_bf16 v[2:17], v[38:41], v[42:45], v[2:17]
	s_cbranch_scc1 .LBB0_553
	s_cmp_eq_u32 s90, 0
	s_cbranch_scc1 .LBB0_556
	s_lshl_b32 s72, s59, 8
	s_lshl_b32 s77, s59, 15
	s_sub_i32 s59, s72, 32
	v_add_u32_e32 v34, s72, v204
	s_lshl_b32 s72, s58, 7
	s_sub_i32 s72, s77, s72
	s_add_i32 s93, s86, s91
	v_subrev_u32_e32 v165, s58, v34
	v_add_u32_e32 v167, s72, v205
	s_sub_i32 s77, s59, s58
	s_nop 7
	v_mov_b64_e32 v[34:35], v[2:3]
	v_mov_b64_e32 v[36:37], v[4:5]
	v_mov_b64_e32 v[38:39], v[6:7]
	v_mov_b64_e32 v[40:41], v[8:9]
	v_mov_b64_e32 v[42:43], v[10:11]
	v_mov_b64_e32 v[44:45], v[12:13]
	v_mov_b64_e32 v[46:47], v[14:15]
	v_mov_b64_e32 v[48:49], v[16:17]
	v_mov_b64_e32 v[50:51], v[18:19]
	v_mov_b64_e32 v[52:53], v[20:21]
	v_mov_b64_e32 v[54:55], v[22:23]
	v_mov_b64_e32 v[56:57], v[24:25]
	v_mov_b64_e32 v[58:59], v[26:27]
	v_mov_b64_e32 v[60:61], v[28:29]
	v_mov_b64_e32 v[62:63], v[30:31]
	v_mov_b64_e32 v[64:65], v[32:33]
	s_branch .LBB0_545

.LBB0_545:
	s_add_i32 s72, s87, s59
	v_mov_b32_e32 v195, v131
	s_cmp_lt_i32 s72, s58
	s_mov_b32 s72, s93
	s_cbranch_scc1 .LBB0_544
	v_add_u32_e32 v2, s87, v165
	v_lshrrev_b32_e32 v26, 1, v2
	v_bitop3_b32 v2, v26, v1, 7 bitop3:0x6c
	v_lshl_add_u32 v2, v2, 4, v167
	ds_read_b128 v[2:5], v2
	s_add_i32 s80, s87, s77
	s_lshr_b32 s80, s80, 2
	v_bitop3_b32 v6, s80, v142, v1 bitop3:0x36
	v_lshlrev_b32_e32 v28, 3, v6
	v_bitop3_b32 v6, v26, v143, 7 bitop3:0x6c
	v_lshl_add_u32 v6, v6, 4, v167
	ds_read_b128 v[18:21], v6
	v_or_b32_e32 v27, s80, v1
	s_waitcnt lgkmcnt(1)
	v_mfma_f32_32x32x16_bf16 v[2:17], v[2:5], v[114:117], 0
	v_bitop3_b32 v22, v27, v142, 2 bitop3:0x36
	v_lshlrev_b32_e32 v30, 3, v22
	v_bitop3_b32 v22, v27, v142, 4 bitop3:0x36
	v_lshlrev_b32_e32 v32, 3, v22
	v_bitop3_b32 v22, v26, v147, 7 bitop3:0x6c
	v_lshl_add_u32 v22, v22, 4, v167
	ds_read_b128 v[22:25], v22
	s_waitcnt lgkmcnt(1)
	v_mfma_f32_32x32x16_bf16 v[2:17], v[18:21], v[118:121], v[2:17]
	v_bitop3_b32 v18, v27, v142, 6 bitop3:0x36
	v_lshlrev_b32_e32 v27, 3, v18
	v_bitop3_b32 v18, v26, v149, 7 bitop3:0x6c
	v_lshl_add_u32 v18, v18, 4, v167
	ds_read_b128 v[18:21], v18
	v_add_u32_e32 v29, v202, v28
	v_add_u32_e32 v132, v202, v27
	s_waitcnt lgkmcnt(1)
	v_mfma_f32_32x32x16_bf16 v[2:17], v[22:25], v[122:125], v[2:17]
	v_add_u32_e32 v22, v203, v28
	v_add_u32_e32 v31, v202, v30
	v_add_u32_e32 v33, v202, v32
	ds_read_b64 v[138:139], v29 offset:49152
	ds_read_b64 v[140:141], v31 offset:49152
	ds_read_b64 v[130:131], v33 offset:49152
	ds_read_b64 v[132:133], v132 offset:49152
	v_add_u32_e32 v23, v203, v30
	v_add_u32_e32 v24, v203, v32
	v_add_u32_e32 v25, v203, v27
	s_waitcnt lgkmcnt(4)
	v_mfma_f32_32x32x16_bf16 v[2:17], v[18:21], v[126:129], v[2:17]
	ds_read_b64 v[218:219], v22 offset:24576
	ds_read_b64 v[220:221], v23 offset:24576
	ds_read_b64 v[134:135], v24 offset:24576
	ds_read_b64 v[136:137], v25 offset:24576
	s_add_i32 s90, s90, -1
	s_nop 6
	v_min_f32_e64 v3, -v3, s98
	v_exp_f32_e32 v3, v3
	v_min_f32_e64 v5, -v5, s98
	v_min_f32_e64 v4, -v4, s98
	v_add_f32_e32 v19, 1.0, v3
	v_exp_f32_e32 v194, v5
	v_min_f32_e64 v5, -v6, s98
	v_rcp_f32_e32 v169, v19
	v_exp_f32_e32 v4, v4
	v_exp_f32_e32 v6, v5
	v_min_f32_e64 v5, -v7, s98
	v_exp_f32_e32 v7, v5
	v_mul_f32_e32 v20, v3, v169
	v_add_f32_e32 v3, 1.0, v4
	v_rcp_f32_e32 v22, v3
	v_add_f32_e32 v3, 1.0, v194
	v_rcp_f32_e32 v24, v3
	v_add_f32_e32 v3, 1.0, v6
	v_rcp_f32_e32 v26, v3
	v_add_f32_e32 v3, 1.0, v7
	v_rcp_f32_e32 v27, v3
	v_min_f32_e64 v3, -v8, s98
	v_exp_f32_e32 v8, v3
	v_min_f32_e64 v3, -v9, s98
	v_exp_f32_e32 v9, v3
	v_add_f32_e32 v3, 1.0, v8
	v_rcp_f32_e32 v28, v3
	v_min_f32_e64 v5, -v12, s98
	v_add_f32_e32 v3, 1.0, v9
	v_rcp_f32_e32 v29, v3
	v_min_f32_e64 v3, -v10, s98
	v_exp_f32_e32 v10, v3
	v_min_f32_e64 v3, -v11, s98
	v_exp_f32_e32 v11, v5
	v_min_f32_e64 v5, -v13, s98
	v_exp_f32_e32 v31, v5
	v_min_f32_e64 v5, -v14, s98
	v_exp_f32_e32 v30, v3
	v_exp_f32_e32 v12, v5
	v_min_f32_e64 v5, -v15, s98
	v_exp_f32_e32 v14, v5
	v_min_f32_e64 v5, -v16, s98
	v_add_f32_e32 v3, 1.0, v10
	v_rcp_f32_e32 v226, v3
	v_add_f32_e32 v3, 1.0, v30
	v_exp_f32_e32 v13, v5
	v_min_f32_e64 v5, -v17, s98
	v_rcp_f32_e32 v228, v3
	v_add_f32_e32 v3, 1.0, v11
	v_rcp_f32_e32 v227, v3
	v_add_f32_e32 v3, 1.0, v31
	v_exp_f32_e32 v15, v5
	v_rcp_f32_e32 v229, v3
	v_add_f32_e32 v3, 1.0, v12
	v_rcp_f32_e32 v230, v3
	v_add_f32_e32 v3, 1.0, v14
	v_rcp_f32_e32 v16, v3
	v_add_f32_e32 v3, 1.0, v13
	v_rcp_f32_e32 v231, v3
	v_add_f32_e32 v3, 1.0, v15
	v_rcp_f32_e32 v17, v3
	v_min_f32_e64 v2, -v2, s98
	v_exp_f32_e32 v2, v2
	v_pk_mul_f32 v[12:13], v[12:13], v[230:231]
	v_pk_mul_f32 v[14:15], v[14:15], v[16:17]
	v_pk_mul_f32 v[6:7], v[6:7], v[26:27]
	v_pk_mul_f32 v[224:225], v[12:13], v[14:15]
	v_add_f32_e32 v18, 1.0, v2
	v_mul_f32_e32 v3, v224, v225
	v_mov_b32_e32 v238, v3
	v_mov_b32_e32 v5, v3
	s_nop 1
	v_permlane32_swap_b32_e32 v238, v5
	s_nop 0
	v_cndmask_b32_e64 v5, v238, v5, s[0:1]
	v_rcp_f32_e32 v18, v18
	v_pk_mul_f32 v[8:9], v[8:9], v[28:29]
	v_pk_mul_f32 v[10:11], v[10:11], v[226:227]
	v_pk_mul_f32 v[232:233], v[30:31], v[228:229]
	v_pk_mul_f32 v[32:33], v[6:7], v[6:7] op_sel_hi:[0,1]
	v_pk_mul_f32 v[222:223], v[8:9], v[8:9] op_sel_hi:[0,1]
	v_pk_mul_f32 v[30:31], v[10:11], v[232:233]
	s_waitcnt lgkmcnt(0)
; __device__ __forceinline__ void attn_phase(LAS unsigned char* lds, const bf16_t* Q, const bf16_t* Kb, const bf16_t* VT, const bf16_t* Zs, bf16_t* OZ, int vcu, int G) {
;     ...
;         int kt = qb; bool done = false;
;     ...
;             ATT_TILE(true)
;             if (__all(carry < STOP)) { done = true; break; }
;         }
	v_mul_f32_e32 v25, v3, v5
	v_pk_mul_f32 v[30:31], v[30:31], v[30:31] op_sel:[0,1] op_sel_hi:[1,0]
	v_mov_b32_e32 v3, v33
	v_mov_b32_e32 v19, v223
	v_mov_b32_e32 v238, v30
	v_mov_b32_e32 v23, v30
	s_nop 1
	v_permlane32_swap_b32_e32 v238, v23
	s_nop 0
	v_cndmask_b32_e64 v23, v238, v23, s[0:1]
	v_pk_mul_f32 v[2:3], v[2:3], v[18:19]
	v_mul_f32_e32 v6, v195, v5
	v_mov_b32_e32 v238, v3
	v_mov_b32_e32 v21, v3
	s_nop 1
	v_permlane32_swap_b32_e32 v238, v21
	s_nop 0
	v_cndmask_b32_e64 v21, v238, v21, s[0:1]
	v_cndmask_b32_e64 v225, v195, v6, s[0:1]
	v_mul_f32_e32 v224, v15, v225
	v_mul_f32_e32 v13, v13, v224
	v_mov_b32_e32 v5, v30
	v_mul_f32_e32 v12, v14, v13
	v_pk_mul_f32 v[14:15], v[194:195], v[24:25]
	s_waitcnt lgkmcnt(1)
	v_pk_mul_f32 v[4:5], v[4:5], v[22:23]
	v_mov_b32_e32 v234, v231
	v_mov_b32_e32 v235, v17
	v_mov_b32_e32 v231, v16
	v_pk_mul_f32 v[16:17], v[4:5], v[14:15]
	s_waitcnt lgkmcnt(0)
	v_pk_mul_f32 v[2:3], v[2:3], v[20:21]
	v_mul_f32_e32 v10, v15, v23
	v_pk_mul_f32 v[236:237], v[2:3], v[16:17]
	v_mov_b32_e32 v238, v236
	v_mov_b32_e32 v171, v236
	s_nop 1
	v_permlane32_swap_b32_e32 v238, v171
	s_nop 0
	v_cndmask_b32_e64 v171, v238, v171, s[0:1]
	v_mul_f32_e32 v2, v17, v21
	v_cndmask_b32_e64 v3, v17, v2, s[0:1]
	v_mul_f32_e32 v2, v9, v3
	v_pk_mul_f32 v[16:17], v[28:29], v[2:3]
	v_mul_f32_e32 v3, v8, v2
	s_waitcnt lgkmcnt(0)
	v_mul_f32_e32 v5, v237, v171
	v_mul_f32_e32 v2, v7, v3
	v_cndmask_b32_e64 v7, v237, v5, s[0:1]
	v_mul_f32_e32 v6, v14, v7
	v_mul_f32_e32 v5, v4, v6
	v_pk_mul_f32 v[2:3], v[26:27], v[2:3]
	v_mov_b32_e32 v23, v24
	v_mul_f32_e32 v4, v20, v5
	v_mov_b32_e32 v19, v169
	v_pk_mul_f32 v[234:235], v[234:235], v[224:225]
	v_pk_mul_f32 v[8:9], v[22:23], v[6:7]
	v_pk_mul_f32 v[4:5], v[18:19], v[4:5]
	v_cvt_pk_bf16_f32 v224, v2, v3
	v_cndmask_b32_e64 v3, v15, v10, s[0:1]
	v_cvt_pk_bf16_f32 v222, v4, v5
	v_cvt_pk_bf16_f32 v223, v8, v9
	v_cvt_pk_bf16_f32 v225, v16, v17
	v_mul_f32_e32 v2, v233, v3
	v_mov_b32_e32 v4, v227
	v_mov_b32_e32 v5, v229
	v_mfma_f32_32x32x16_bf16 v[50:65], v[138:141], v[222:225], v[50:65]
	v_mul_f32_e64 v140, v230, v12
	v_mul_f32_e64 v141, v231, v13
	v_mul_f32_e64 v230, v4, v2
	v_mul_f32_e64 v231, v5, v3
	v_mul_f32_e32 v139, v11, v2
	v_mul_f32_e32 v138, v232, v139
	v_mov_b32_e32 v227, v228
	v_pk_mul_f32 v[138:139], v[226:227], v[138:139]
	v_cvt_pk_bf16_f32 v140, v140, v141
	v_mfma_f32_32x32x16_bf16 v[34:49], v[218:221], v[222:225], v[34:49]
	v_cvt_pk_bf16_f32 v138, v138, v139
	v_cvt_pk_bf16_f32 v139, v230, v231
	v_cvt_pk_bf16_f32 v141, v234, v235
	s_nop 1
	v_mfma_f32_32x32x16_bf16 v[50:65], v[130:133], v[138:141], v[50:65]
	v_mul_f32_e32 v130, v236, v171
	v_mul_f32_e32 v131, v130, v237
	v_cmp_gt_f32_e32 vcc, s88, v131
	s_cmp_lg_u64 vcc, exec
	v_mfma_f32_32x32x16_bf16 v[34:49], v[134:137], v[138:141], v[34:49]
	s_cbranch_scc0 .LBB0_548
	s_add_i32 s93, s72, -1
	s_sub_i32 s77, s77, 32
	s_sub_i32 s59, s59, 32
	s_cmp_lt_i32 s93, 2
	s_mov_b32 s94, -1
	v_subrev_u32_e32 v165, 32, v165
	v_add_u32_e32 v167, 0xfffff000, v167
	s_cselect_b64 s[80:81], -1, 0
	s_mov_b64 s[82:83], 0
	s_and_b64 vcc, exec, s[80:81]
	s_cbranch_vccz .LBB0_545
	s_branch .LBB0_549

; __global__ void __launch_bounds__(NTHR, 2) hybrid_fwd(Args a) {
	.amdhsa_kernel _Z10hybrid_fwd4Args
		.amdhsa_group_segment_fixed_size 0
		.amdhsa_private_segment_fixed_size 0
		.amdhsa_kernarg_size 400
		.amdhsa_user_sgpr_count 2
		.amdhsa_user_sgpr_dispatch_ptr 0
		.amdhsa_user_sgpr_queue_ptr 0
		.amdhsa_user_sgpr_kernarg_segment_ptr 1
		.amdhsa_user_sgpr_dispatch_id 0
		.amdhsa_user_sgpr_kernarg_preload_length 0
		.amdhsa_user_sgpr_kernarg_preload_offset 0
		.amdhsa_user_sgpr_private_segment_size 0
		.amdhsa_uses_dynamic_stack 0
		.amdhsa_enable_private_segment 0
		.amdhsa_system_sgpr_workgroup_id_x 1
		.amdhsa_system_sgpr_workgroup_id_y 0
		.amdhsa_system_sgpr_workgroup_id_z 0
		.amdhsa_system_sgpr_workgroup_info 0
		.amdhsa_system_vgpr_workitem_id 0
		.amdhsa_next_free_vgpr 256
		.amdhsa_next_free_sgpr 100
		.amdhsa_accum_offset 256
		.amdhsa_reserve_vcc 1
		.amdhsa_float_round_mode_32 0
		.amdhsa_float_round_mode_16_64 0
		.amdhsa_float_denorm_mode_32 3
		.amdhsa_float_denorm_mode_16_64 3
		.amdhsa_dx10_clamp 1
		.amdhsa_ieee_mode 1
		.amdhsa_fp16_overflow 0
		.amdhsa_tg_split 0
		.amdhsa_exception_fp_ieee_invalid_op 0
		.amdhsa_exception_fp_denorm_src 0
		.amdhsa_exception_fp_ieee_div_zero 0
		.amdhsa_exception_fp_ieee_overflow 0
		.amdhsa_exception_fp_ieee_underflow 0
		.amdhsa_exception_fp_ieee_inexact 0
		.amdhsa_exception_int_div_zero 0
	.end_amdhsa_kernel

; __global__ void __launch_bounds__(NTHR, 2) hybrid_fwd(Args a) {
amdhsa.kernels:
  - .agpr_count:     0
    .args:
      - .offset:         0
        .size:           144
        .value_kind:     by_value
      - .offset:         144
        .size:           4
        .value_kind:     hidden_block_count_x
      - .offset:         148
        .size:           4
        .value_kind:     hidden_block_count_y
      - .offset:         152
        .size:           4
        .value_kind:     hidden_block_count_z
      - .offset:         156
        .size:           2
        .value_kind:     hidden_group_size_x
      - .offset:         158
        .size:           2
        .value_kind:     hidden_group_size_y
      - .offset:         160
        .size:           2
        .value_kind:     hidden_group_size_z
      - .offset:         162
        .size:           2
        .value_kind:     hidden_remainder_x
      - .offset:         164
        .size:           2
        .value_kind:     hidden_remainder_y
      - .offset:         166
        .size:           2
        .value_kind:     hidden_remainder_z
      - .offset:         184
        .size:           8
        .value_kind:     hidden_global_offset_x
      - .offset:         192
        .size:           8
        .value_kind:     hidden_global_offset_y
      - .offset:         200
        .size:           8
        .value_kind:     hidden_global_offset_z
      - .offset:         208
        .size:           2
        .value_kind:     hidden_grid_dims
      - .offset:         264
        .size:           4
        .value_kind:     hidden_dynamic_lds_size
    .group_segment_fixed_size: 0
    .kernarg_segment_align: 8
    .kernarg_segment_size: 400
    .language:       OpenCL C
    .language_version:
      - 2
      - 0
    .max_flat_workgroup_size: 512
    .name:           _Z10hybrid_fwd4Args
    .private_segment_fixed_size: 0
    .sgpr_count:     106
    .sgpr_spill_count: 2
    .symbol:         _Z10hybrid_fwd4Args.kd
    .uniform_work_group_size: 1
    .uses_dynamic_stack: false
    .vgpr_count:     256
    .vgpr_spill_count: 0
    .wavefront_size: 64
